# p0: the small tables are built by workgroup 255 instead of workgroup 0 (which also builds SC rows), on top of v13
# baseline (speedup 1.0000x reference)
.LBB0_793:
	s_or_b64 exec, exec, s[4:5]
	s_cmp_lg_u32 s35, 0xff
	s_cbranch_scc1 .LBB0_801
	s_movk_i32 s4, 0x203
	v_cmp_lt_i32_e32 vcc, s4, v214
	v_ashrrev_i32_e32 v215, 31, v214
	s_and_saveexec_b64 s[4:5], vcc
	s_xor_b64 s[4:5], exec, s[4:5]
	s_andn2_saveexec_b64 s[4:5], s[4:5]
	s_cbranch_execz .LBB0_800
	v_readlane_b32 s10, v252, 0
	v_readlane_b32 s11, v252, 1
	s_lshl_b64 s[6:7], s[10:11], 3
	s_add_u32 s6, s94, s6
	s_addc_u32 s7, s95, s7
	s_load_dwordx2 s[6:7], s[6:7], 0x40
	v_readlane_b32 s8, v250, 59
	s_add_u32 s8, s8, s10
	v_readlane_b32 s9, v251, 0
	s_addc_u32 s9, s9, s11
	v_and_b32_e32 v2, 3, v214
	v_lshl_add_u64 v[0:1], v[214:215], 2, s[8:9]
	s_mov_b64 s[8:9], 0
	v_mov_b32_e32 v3, v214
	s_branch .LBB0_797
